# neighbourhood-attention units: row-group index rotated per round so every workgroup gets exactly one short (image-edge) unit instead of some getting eight
# baseline (speedup 1.0000x reference)
.LBB0_701:
	s_andn2_b64 vcc, exec, s[4:5]
	s_mov_b32 s1, s20
	s_cbranch_vccnz .LBB0_703
	s_ashr_i32 s0, s20, 3
	s_andn2_b32 s0, s0, 31
	v_readlane_b32 s3, v255, 13
	s_add_i32 s0, s0, s3
	s_ashr_i32 s0, s0, 4
	v_readlane_b32 s1, v255, 12
	s_add_i32 s1, s0, s1
	s_ashr_i32 s12, s1, 4
	s_lshr_b32 s4, s20, 7
	s_andn2_b32 s4, s4, 1
	s_add_i32 s1, s3, s4
